# v035 + MLA sample attention loop: first K-fragment LDS reads issued right after the tile barrier, before the next-tile LDS-DMA issue block
# speedup vs baseline: 1.0064x; 1.0033x over previous
.LBB0_1580:
	s_cmpk_gt_u32 s58, 0x45
	s_waitcnt lgkmcnt(0)
	s_barrier
	s_lshl_b32 s6, s57, 14
	v_add_u32_e32 v185, s6, v169
	v_mov_b32_e32 v222, v157
	s_nop 0
	v_xad_u32 v70, v222, v158, v185
	v_xad_u32 v74, v222, v162, v185
	ds_read_b128 v[66:69], v70
	ds_read_b128 v[70:73], v70 offset:8192
	ds_read_b128 v[186:189], v74
	ds_read_b128 v[190:193], v74 offset:8192
	v_xad_u32 v74, v222, v159, v185
	ds_read_b128 v[194:197], v74
	ds_read_b128 v[198:201], v74 offset:8192
	v_xad_u32 v74, v222, v163, v185
	ds_read_b128 v[202:205], v74
	ds_read_b128 v[206:209], v74 offset:8192
	s_cmpk_gt_u32 s58, 0x45
	s_cbranch_scc1 .Lmla_skipw
	v_sub_co_u32_e64 v238, s[2:3], s57, 1
	s_cmp_lt_u32 s58, 6
	s_nop 0
	v_cndmask_b32_e64 v240, v238, 2, s[2:3]
	s_cselect_b64 s[2:3], -1, 0
	s_and_b64 s[2:3], s[2:3], exec
	s_cselect_b32 s6, 2, -6
	s_cselect_b32 s26, s21, s25
	s_cselect_b32 s27, s20, s24
	s_cselect_b32 s3, s19, s23
	s_cselect_b32 s2, s18, s22
	s_add_i32 s6, s6, s58
	s_add_u32 s59, s36, s27
	s_addc_u32 s60, s37, s26
	s_lshl_b64 s[2:3], s[2:3], 1
	s_add_u32 s61, s51, s2
	s_addc_u32 s62, s54, s3
	s_add_u32 s26, s55, s2
	s_addc_u32 s27, s56, s3
	s_lshl_b64 s[2:3], s[6:7], 18
	s_add_u32 s26, s26, s2
	v_lshl_add_u32 v241, v240, 14, v167
	s_addc_u32 s27, s27, s3
	v_add_u32_e32 v242, 0xc000, v241
	v_lshl_add_u64 v[238:239], s[26:27], 0, v[132:133]
	v_readfirstlane_b32 s26, v242
	v_add_u32_e32 v242, 0xe000, v241
	s_add_u32 s2, s61, s2
	s_mov_b32 m0, s26
	v_readfirstlane_b32 s26, v242
	s_addc_u32 s3, s62, s3
	global_load_lds_dwordx4 v[238:239], off
	v_lshl_add_u64 v[238:239], v[238:239], 0, s[8:9]
	s_mov_b32 m0, s26
	v_lshl_add_u32 v240, v240, 13, v168
	global_load_lds_dwordx4 v[238:239], off
	v_lshl_add_u64 v[238:239], s[2:3], 0, v[134:135]
	v_readfirstlane_b32 s2, v241
	v_add_u32_e32 v241, 0x2000, v241
	s_mov_b32 m0, s2
	v_readfirstlane_b32 s2, v241
	global_load_lds_dwordx4 v[238:239], off
	s_mov_b32 m0, s2
	s_lshl_b64 s[2:3], s[6:7], 13
	s_add_u32 s2, s59, s2
	v_lshl_add_u64 v[238:239], v[238:239], 0, s[8:9]
	s_addc_u32 s3, s60, s3
	global_load_lds_dwordx4 v[238:239], off
	v_lshl_add_u64 v[238:239], s[2:3], 0, v[136:137]
	v_readfirstlane_b32 s2, v240
	s_mov_b32 m0, s2
	s_nop 0
	global_load_lds_dwordx4 v[238:239], off
.Lmla_skipw:
	s_lshl_b32 s6, s57, 14
	s_waitcnt lgkmcnt(0)
	v_mfma_f32_32x32x16_bf16 v[82:97], v[66:69], v[98:101], 0
	v_xad_u32 v210, v222, v160, v185
	v_xad_u32 v218, v222, v164, v185
	v_mfma_f32_32x32x16_bf16 v[66:81], v[70:73], v[98:101], 0
	v_mfma_f32_32x32x16_bf16 v[82:97], v[186:189], v[102:105], v[82:97]
	ds_read_b128 v[186:189], v210
	ds_read_b128 v[210:213], v210 offset:8192
	ds_read_b128 v[214:217], v218
	ds_read_b128 v[218:221], v218 offset:8192
	v_mfma_f32_32x32x16_bf16 v[66:81], v[190:193], v[102:105], v[66:81]
	v_mfma_f32_32x32x16_bf16 v[82:97], v[194:197], v[106:109], v[82:97]
	v_xad_u32 v194, v222, v161, v185
	v_xad_u32 v185, v222, v165, v185
	ds_read_b128 v[190:193], v194
	ds_read_b128 v[194:197], v194 offset:8192
	v_mfma_f32_32x32x16_bf16 v[66:81], v[198:201], v[106:109], v[66:81]
	v_mfma_f32_32x32x16_bf16 v[82:97], v[202:205], v[110:113], v[82:97]
	ds_read_b128 v[198:201], v185
	ds_read_b128 v[202:205], v185 offset:8192
	v_mfma_f32_32x32x16_bf16 v[66:81], v[206:209], v[110:113], v[66:81]
	s_waitcnt lgkmcnt(0)
	v_mfma_f32_32x32x16_bf16 v[82:97], v[186:189], v[114:117], v[82:97]
	v_lshl_add_u32 v185, s57, 13, v170
	v_mov_b32_e32 v230, v153
	v_mov_b32_e32 v234, v171
	s_nop 0
	v_bitop3_b32 v186, v230, v152, 7 bitop3:0x6c
	v_mfma_f32_32x32x16_bf16 v[66:81], v[210:213], v[114:117], v[66:81]
	v_lshlrev_b32_e32 v210, 4, v186
	v_add_u32_e32 v206, v210, v185
	v_add_u32_e32 v210, v210, v234
	ds_read_b128 v[186:189], v206
	ds_read_b128 v[206:209], v206 offset:4096
	ds_read_b128 v[210:213], v210
	v_mfma_f32_32x32x16_bf16 v[82:97], v[214:217], v[118:121], v[82:97]
	v_bitop3_b32 v214, v230, v154, 7 bitop3:0x6c
	v_lshlrev_b32_e32 v226, 4, v214
	v_add_u32_e32 v222, v226, v185
	ds_read_b128 v[214:217], v222
	ds_read_b128 v[222:225], v222 offset:4096
	v_add_u32_e32 v226, v226, v234
	ds_read_b128 v[226:229], v226
	v_mfma_f32_32x32x16_bf16 v[66:81], v[218:221], v[118:121], v[66:81]
	v_mfma_f32_32x32x16_bf16 v[82:97], v[190:193], v[122:125], v[82:97]
	v_bitop3_b32 v190, v230, v155, 7 bitop3:0x6c
	v_lshlrev_b32_e32 v218, 4, v190
	v_mfma_f32_32x32x16_bf16 v[66:81], v[194:197], v[122:125], v[66:81]
	v_add_u32_e32 v194, v218, v185
	v_add_u32_e32 v218, v218, v234
	ds_read_b128 v[190:193], v194
	ds_read_b128 v[194:197], v194 offset:4096
	ds_read_b128 v[218:221], v218
	v_mfma_f32_32x32x16_bf16 v[82:97], v[198:201], v[126:129], v[82:97]
	v_bitop3_b32 v198, v230, v156, 7 bitop3:0x6c
	v_lshlrev_b32_e32 v235, 4, v198
	v_add_u32_e32 v185, v235, v185
	ds_read_b128 v[198:201], v185
	ds_read_b128 v[230:233], v185 offset:4096
	v_add_u32_e32 v185, v235, v234
	ds_read_b128 v[234:237], v185
	v_mfma_f32_32x32x16_bf16 v[66:81], v[202:205], v[126:129], v[66:81]
	s_waitcnt lgkmcnt(0)
	v_mfma_f32_32x32x16_bf16 v[82:97], v[186:189], v[210:213], v[82:97]
	v_mfma_f32_32x32x16_bf16 v[66:81], v[206:209], v[210:213], v[66:81]
	v_mfma_f32_32x32x16_bf16 v[82:97], v[214:217], v[226:229], v[82:97]
	v_mfma_f32_32x32x16_bf16 v[66:81], v[222:225], v[226:229], v[66:81]
	v_mfma_f32_32x32x16_bf16 v[82:97], v[190:193], v[218:221], v[82:97]
	v_mfma_f32_32x32x16_bf16 v[66:81], v[194:197], v[218:221], v[66:81]
	v_mfma_f32_32x32x16_bf16 v[82:97], v[198:201], v[234:237], v[82:97]
	v_mfma_f32_32x32x16_bf16 v[66:81], v[230:233], v[234:237], v[66:81]
	s_nop 10
	v_max_f32_e32 v185, v83, v83
	v_max_f32_e32 v186, v82, v82
	v_max_f32_e32 v185, v186, v185
	v_max3_f32 v185, v185, v84, v85
	v_max3_f32 v185, v185, v86, v87
	v_max3_f32 v185, v185, v88, v89
	v_max3_f32 v185, v185, v90, v91
	v_max3_f32 v185, v185, v92, v93
	v_max3_f32 v185, v185, v94, v95
	v_max3_f32 v185, v185, v96, v97
	v_max3_f32 v185, v185, v66, v67
	v_max3_f32 v185, v185, v68, v69
	v_max3_f32 v185, v185, v70, v71
	v_max3_f32 v185, v185, v72, v73
	v_max3_f32 v185, v185, v74, v75
	v_max3_f32 v185, v185, v76, v77
	v_max3_f32 v185, v185, v78, v79
	v_max3_f32 v185, v185, v80, v81
	v_mov_b32_e32 v186, v185
	s_nop 1
	v_permlane32_swap_b32_e32 v185, v186
	v_max_f32_e32 v186, v186, v186
	v_max_f32_e32 v185, v185, v185
	v_max_f32_e32 v185, v185, v186
	v_max_f32_e32 v186, v139, v139
	v_max_f32_e32 v186, v186, v185
	v_sub_f32_e32 v187, v185, v139
	v_sub_f32_e32 v185, v139, v186
	v_mul_f32_e32 v185, 0x3dd53b94, v185
	v_exp_f32_e32 v185, v185
	v_cmp_ge_f32_e32 vcc, s45, v187
	s_cmp_eq_u64 vcc, exec
	s_cselect_b64 s[2:3], -1, 0
	v_cndmask_b32_e64 v185, v185, 1.0, s[2:3]
	v_cmp_gt_f32_e32 vcc, 1.0, v185
	s_cbranch_vccz .LBB0_1586
	s_and_saveexec_b64 s[26:27], s[0:1]
	ds_write_b32 v172, v185 offset:128
	s_or_b64 exec, exec, s[26:27]
	s_waitcnt lgkmcnt(0)
	ds_read_b128 v[188:191], v173 offset:224
	ds_read_b128 v[192:195], v173 offset:192
	ds_read_b128 v[196:199], v173 offset:160
	ds_read_b128 v[200:203], v173 offset:128
	s_waitcnt lgkmcnt(0)
	v_pk_mul_f32 v[16:17], v[16:17], v[190:191]
	v_pk_mul_f32 v[12:13], v[12:13], v[194:195]
	v_pk_mul_f32 v[8:9], v[8:9], v[198:199]
	v_pk_mul_f32 v[4:5], v[4:5], v[202:203]
	v_pk_mul_f32 v[14:15], v[14:15], v[188:189]
	v_pk_mul_f32 v[10:11], v[10:11], v[192:193]
	v_pk_mul_f32 v[6:7], v[6:7], v[196:197]
	v_pk_mul_f32 v[2:3], v[2:3], v[200:201]
	v_pk_mul_f32 v[64:65], v[64:65], v[190:191]
	v_pk_mul_f32 v[60:61], v[60:61], v[194:195]
	v_pk_mul_f32 v[56:57], v[56:57], v[198:199]
	v_pk_mul_f32 v[52:53], v[52:53], v[202:203]
	v_pk_mul_f32 v[62:63], v[62:63], v[188:189]
	v_pk_mul_f32 v[58:59], v[58:59], v[192:193]
	v_pk_mul_f32 v[54:55], v[54:55], v[196:197]
	v_pk_mul_f32 v[50:51], v[50:51], v[200:201]
	v_pk_mul_f32 v[48:49], v[48:49], v[190:191]
	v_pk_mul_f32 v[44:45], v[44:45], v[194:195]
	v_pk_mul_f32 v[40:41], v[40:41], v[198:199]
	v_pk_mul_f32 v[36:37], v[36:37], v[202:203]
	v_pk_mul_f32 v[46:47], v[46:47], v[188:189]
	v_pk_mul_f32 v[42:43], v[42:43], v[192:193]
	v_pk_mul_f32 v[38:39], v[38:39], v[196:197]
	v_pk_mul_f32 v[34:35], v[34:35], v[200:201]
	v_pk_mul_f32 v[32:33], v[32:33], v[190:191]
	v_pk_mul_f32 v[28:29], v[28:29], v[194:195]
	v_pk_mul_f32 v[24:25], v[24:25], v[198:199]
	v_pk_mul_f32 v[20:21], v[20:21], v[202:203]
	v_pk_mul_f32 v[30:31], v[30:31], v[188:189]
	v_pk_mul_f32 v[26:27], v[26:27], v[192:193]
	v_pk_mul_f32 v[22:23], v[22:23], v[196:197]
	v_pk_mul_f32 v[18:19], v[18:19], v[200:201]
